# attention: three staging-register cvts moved behind the last QK MFMA (v18 variant)
# baseline (speedup 1.0000x reference)
; __device__ __forceinline__ void finishSM(f32x16& p0, f32x16& p1, float alpha, float& l_reg, bf16x8& pa0, bf16x8& pa1, bf16x8& pa2, bf16x8& pa3) {
;   for (int r = 0; r < 16; ++r) p1[r] = __builtin_amdgcn_exp2f(p1[r]);
;   float ps = 0; for (int r = 0; r < 16; ++r) ps += p0[r]; for (int r = 0; r < 16; ++r) ps += p1[r];
;   { auto rr = __builtin_amdgcn_permlane32_swap(__float_as_uint(ps), __float_as_uint(ps), false, false);
;     ps = __uint_as_float(rr[0]) + __uint_as_float(rr[1]); }
;   l_reg = l_reg * alpha + ps;
;     ...
;   PK4(p0, 0, pa0); PK4(p0, 8, pa1); PK4(p1, 0, pa2); PK4(p1, 8, pa3);
;     ...
; }
; __device__ __forceinline__ void qkt(f32x16& p0, f32x16& p1, const bf16* Ks, const bf16x8* qr, int r32, int hi) {
;   p0 = f32x16{}; p1 = f32x16{};
;   for (int d0 = 0; d0 < 8; ++d0) { int cb = (d0 * 16 + hi * 8) * 2;
;     bf16x8 b0 = *reinterpret_cast<const bf16x8*>((const char*)Ks + KSWZ(r32, cb));
;     bf16x8 b1 = *reinterpret_cast<const bf16x8*>((const char*)Ks + KSWZ(32 + r32, cb));
;     p0 = __builtin_amdgcn_mfma_f32_32x32x16_bf16(b0, qr[d0], p0, 0, 0, 0);
;     p1 = __builtin_amdgcn_mfma_f32_32x32x16_bf16(b1, qr[d0], p1, 0, 0, 0); }
; }
.LBB0_575:
	ds_read_b128 v[64:67], v189 offset:49152
	ds_read_b128 v[68:71], v189 offset:57344
	ds_read_b128 v[210:213], v199 offset:49152
	ds_read_b128 v[214:217], v199 offset:57344
	ds_read_b128 v[240:243], v192 offset:49152
	ds_read_b128 v[244:247], v192 offset:57344
	v_add_f32_e32 v160, v175, v161
	s_waitcnt lgkmcnt(5)
	v_mfma_f32_32x32x16_bf16 v[80:95], v[64:67], v[112:115], 0
	v_add_f32_e32 v160, v162, v160
	v_add_f32_e32 v160, v206, v160
	v_add_f32_e32 v160, v174, v160
	v_add_f32_e32 v160, v209, v160
	v_add_f32_e32 v160, v163, v160
	v_add_f32_e32 v160, v173, v160
	v_add_f32_e32 v160, v169, v160
	s_waitcnt lgkmcnt(4)
	v_mfma_f32_32x32x16_bf16 v[64:79], v[68:71], v[112:115], 0
	v_add_f32_e32 v160, v171, v160
	v_add_f32_e32 v160, v170, v160
	v_add_f32_e32 v160, v172, v160
	v_exp_f32_e32 v158, v158
	v_add_f32_e32 v160, v165, v160
	v_exp_f32_e32 v159, v159
	v_add_f32_e32 v160, v167, v160
	s_waitcnt lgkmcnt(3)
	v_mfma_f32_32x32x16_bf16 v[80:95], v[210:213], v[108:111], v[80:95]
	v_exp_f32_e32 v156, v156
	v_add_f32_e32 v160, v166, v160
	v_exp_f32_e32 v157, v157
	v_add_f32_e32 v160, v168, v160
	v_exp_f32_e32 v152, v152
	v_add_f32_e32 v160, v158, v160
	v_exp_f32_e32 v153, v153
	s_waitcnt lgkmcnt(2)
	v_mfma_f32_32x32x16_bf16 v[64:79], v[214:217], v[108:111], v[64:79]
	ds_read_b128 v[210:213], v191 offset:49152
	ds_read_b128 v[214:217], v191 offset:57344
	v_add_f32_e32 v160, v159, v160
	v_exp_f32_e32 v148, v148
	v_add_f32_e32 v160, v156, v160
	v_exp_f32_e32 v149, v149
	v_add_f32_e32 v160, v157, v160
	v_exp_f32_e32 v146, v146
	s_waitcnt lgkmcnt(3)
	v_mfma_f32_32x32x16_bf16 v[80:95], v[240:243], v[120:123], v[80:95]
	v_add_f32_e32 v160, v152, v160
	v_exp_f32_e32 v147, v147
	v_add_f32_e32 v160, v153, v160
	v_exp_f32_e32 v154, v154
	v_add_f32_e32 v160, v148, v160
	v_exp_f32_e32 v155, v155
	v_add_f32_e32 v160, v149, v160
	s_waitcnt lgkmcnt(2)
	v_mfma_f32_32x32x16_bf16 v[64:79], v[244:247], v[120:123], v[64:79]
	ds_read_b128 v[240:243], v189 offset:49280
	ds_read_b128 v[244:247], v189 offset:57472
	v_exp_f32_e32 v150, v150
	v_add_f32_e32 v160, v146, v160
	v_exp_f32_e32 v151, v151
	v_add_f32_e32 v160, v147, v160
	v_exp_f32_e32 v144, v144
	v_add_f32_e32 v160, v154, v160
	s_waitcnt lgkmcnt(3)
	v_mfma_f32_32x32x16_bf16 v[80:95], v[210:213], v[124:127], v[80:95]
	v_exp_f32_e32 v145, v145
	v_add_f32_e32 v160, v155, v160
	v_add_f32_e32 v160, v150, v160
	v_add_f32_e32 v160, v151, v160
	v_add_f32_e32 v160, v144, v160
	v_add_f32_e32 v203, v145, v160
	s_waitcnt lgkmcnt(2)
	v_mfma_f32_32x32x16_bf16 v[64:79], v[214:217], v[124:127], v[64:79]
	ds_read_b128 v[210:213], v199 offset:49280
	ds_read_b128 v[214:217], v199 offset:57472
	s_waitcnt lgkmcnt(3)
	v_mfma_f32_32x32x16_bf16 v[80:95], v[240:243], v[116:119], v[80:95]
	s_waitcnt lgkmcnt(2)
	v_mfma_f32_32x32x16_bf16 v[64:79], v[244:247], v[116:119], v[64:79]
	ds_read_b128 v[240:243], v192 offset:49280
	ds_read_b128 v[244:247], v192 offset:57472
	s_waitcnt lgkmcnt(3)
	v_mfma_f32_32x32x16_bf16 v[80:95], v[210:213], v[104:107], v[80:95]
	s_waitcnt lgkmcnt(2)
	v_mfma_f32_32x32x16_bf16 v[64:79], v[214:217], v[104:107], v[64:79]
	ds_read_b128 v[210:213], v191 offset:49280
	ds_read_b128 v[214:217], v191 offset:57472
	s_waitcnt lgkmcnt(3)
	v_mfma_f32_32x32x16_bf16 v[80:95], v[240:243], v[100:103], v[80:95]
	s_waitcnt lgkmcnt(2)
	v_mfma_f32_32x32x16_bf16 v[64:79], v[244:247], v[100:103], v[64:79]
	v_cvt_pk_bf16_f32 v160, v161, v175
	v_cvt_pk_bf16_f32 v161, v162, v206
	v_cvt_pk_bf16_f32 v162, v174, v209
	v_cvt_pk_bf16_f32 v163, v163, v173
	v_cvt_pk_bf16_f32 v206, v169, v171
	v_cvt_pk_bf16_f32 v207, v170, v172
	s_waitcnt lgkmcnt(1)
	v_mfma_f32_32x32x16_bf16 v[80:95], v[210:213], v[96:99], v[80:95]
	v_cvt_pk_bf16_f32 v208, v165, v167
	v_cvt_pk_bf16_f32 v209, v166, v168
	s_waitcnt lgkmcnt(0)
; #define SBAR() __builtin_amdgcn_sched_barrier(0)
; __device__ __forceinline__ void partialSM(f32x16& p0, f32x16& p1, float& m_reg, float& mn, float& alpha) {
;   constexpr float C = SCALE * 1.4426950408889634f;
;   float pmax = p0[0]; for (int r = 1; r < 16; ++r) pmax = fmaxf(pmax, p0[r]); for (int r = 0; r < 16; ++r) pmax = fmaxf(pmax, p1[r]);
;   { auto rr = __builtin_amdgcn_permlane32_swap(__float_as_uint(pmax), __float_as_uint(pmax), false, false);
;     pmax = fmaxf(__uint_as_float(rr[0]), __uint_as_float(rr[1])); }
;   if (__builtin_expect(__all(pmax - m_reg <= THR / SCALE), 1)) { mn = m_reg; alpha = 1.f; }
;   else { mn = fmaxf(m_reg, pmax); alpha = __builtin_amdgcn_exp2f((m_reg - mn) * C); m_reg = mn; }
; template <int OFF> __device__ __forceinline__ s16x4 tr_read(int vb) {
;   s16x4 r; asm volatile("ds_read_b64_tr_b16 %0, %1 offset:%2" : "=&v"(r) : "v"(vb), "i"(OFF) : "memory"); return r;
; }
; template <int D0> __device__ __forceinline__ void pv_one(f32x16& od, int vb, bf16x8 pa0, bf16x8 pa1, bf16x8 pa2, bf16x8 pa3) {
;   const s16x4 l0 = tr_read<v_rd_off(D0, 0, 0)>(vb), h0 = tr_read<v_rd_off(D0, 0, 1)>(vb), l1 = tr_read<v_rd_off(D0, 1, 0)>(vb), h1 = tr_read<v_rd_off(D0, 1, 1)>(vb);
;   const s16x4 l2 = tr_read<v_rd_off(D0, 2, 0)>(vb), h2 = tr_read<v_rd_off(D0, 2, 1)>(vb), l3 = tr_read<v_rd_off(D0, 3, 0)>(vb), h3 = tr_read<v_rd_off(D0, 3, 1)>(vb);
;   asm volatile("s_waitcnt lgkmcnt(0)" ::: "memory"); SBAR();
;     ...
;   od = __builtin_amdgcn_mfma_f32_32x32x16_bf16(pa0, PK(l0, h0), od, 0, 0, 0);
;   od = __builtin_amdgcn_mfma_f32_32x32x16_bf16(pa1, PK(l1, h1), od, 0, 0, 0);
;   od = __builtin_amdgcn_mfma_f32_32x32x16_bf16(pa2, PK(l2, h2), od, 0, 0, 0);
;   od = __builtin_amdgcn_mfma_f32_32x32x16_bf16(pa3, PK(l3, h3), od, 0, 0, 0);
;     ...
; }
; __device__ __forceinline__ void pv_d0(f32x16* o, int vb, bf16x8 pa0, bf16x8 pa1, bf16x8 pa2, bf16x8 pa3) {
;   pv_one<0>(o[0], vb, pa0, pa1, pa2, pa3); pv_one<1>(o[1], vb, pa0, pa1, pa2, pa3); pv_one<2>(o[2], vb, pa0, pa1, pa2, pa3); pv_one<3>(o[3], vb, pa0, pa1, pa2, pa3);
	v_mfma_f32_32x32x16_bf16 v[64:79], v[214:217], v[96:99], v[64:79]
	v_cvt_pk_bf16_f32 v166, v158, v159
	v_cvt_pk_bf16_f32 v167, v156, v157
	v_cvt_pk_bf16_f32 v168, v152, v153
	v_cvt_pk_bf16_f32 v171, v154, v155
	s_add_u32 s40, s52, 0x18000
	s_addc_u32 s41, s53, 0
	global_load_dwordx4 v[156:159], v176, s[40:41]
	v_cvt_pk_bf16_f32 v169, v148, v149
	global_load_dwordx4 v[152:155], v176, s[40:41] offset:-512
	v_cvt_pk_bf16_f32 v172, v150, v151
	global_load_dwordx4 v[148:151], v176, s[52:53] offset:-512
	v_cvt_pk_bf16_f32 v170, v146, v147
	v_cvt_pk_bf16_f32 v173, v144, v145
	global_load_dwordx4 v[144:147], v176, s[52:53]
	s_add_u32 s52, s52, 0x30000
	s_addc_u32 s53, s53, 0
	ds_read_b64_tr_b16 v[210:211], v184 offset:0
	ds_read_b64_tr_b16 v[212:213], v184 offset:0x800
	ds_read_b64_tr_b16 v[214:215], v184 offset:0x1000
	ds_read_b64_tr_b16 v[216:217], v184 offset:0x1800
	ds_read_b64_tr_b16 v[224:225], v184 offset:0x2000
	ds_read_b64_tr_b16 v[226:227], v184 offset:0x2800
	ds_read_b64_tr_b16 v[228:229], v184 offset:0x3000
	ds_read_b64_tr_b16 v[230:231], v184 offset:0x3800
	s_waitcnt lgkmcnt(0)
	v_mfma_f32_32x32x16_bf16 v[0:15], v[160:163], v[210:213], v[0:15]
	ds_read_b64_tr_b16 v[210:211], v184 offset:0x200
	ds_read_b64_tr_b16 v[212:213], v184 offset:0xa00
	v_mfma_f32_32x32x16_bf16 v[0:15], v[206:209], v[214:217], v[0:15]
	ds_read_b64_tr_b16 v[214:215], v184 offset:0x1200
	ds_read_b64_tr_b16 v[216:217], v184 offset:0x1a00
	v_mfma_f32_32x32x16_bf16 v[0:15], v[166:169], v[224:227], v[0:15]
	ds_read_b64_tr_b16 v[224:225], v184 offset:0x2200
	ds_read_b64_tr_b16 v[226:227], v184 offset:0x2a00
	v_mfma_f32_32x32x16_bf16 v[0:15], v[170:173], v[228:231], v[0:15]
	ds_read_b64_tr_b16 v[228:229], v184 offset:0x3200
	ds_read_b64_tr_b16 v[230:231], v184 offset:0x3a00
	s_waitcnt lgkmcnt(0)
	v_mfma_f32_32x32x16_bf16 v[48:63], v[160:163], v[210:213], v[48:63]
	ds_read_b64_tr_b16 v[210:211], v184 offset:0x400
	ds_read_b64_tr_b16 v[212:213], v184 offset:0xc00
	v_mfma_f32_32x32x16_bf16 v[48:63], v[206:209], v[214:217], v[48:63]
	ds_read_b64_tr_b16 v[214:215], v184 offset:0x1400
	ds_read_b64_tr_b16 v[216:217], v184 offset:0x1c00
	v_mfma_f32_32x32x16_bf16 v[48:63], v[166:169], v[224:227], v[48:63]
	ds_read_b64_tr_b16 v[224:225], v184 offset:0x2400
	ds_read_b64_tr_b16 v[226:227], v184 offset:0x2c00
	v_mfma_f32_32x32x16_bf16 v[48:63], v[170:173], v[228:231], v[48:63]
	ds_read_b64_tr_b16 v[228:229], v184 offset:0x3400
	ds_read_b64_tr_b16 v[230:231], v184 offset:0x3c00
	s_waitcnt lgkmcnt(0)
	v_mfma_f32_32x32x16_bf16 v[32:47], v[160:163], v[210:213], v[32:47]
	ds_read_b64_tr_b16 v[210:211], v184 offset:0x600
	ds_read_b64_tr_b16 v[212:213], v184 offset:0xe00
	v_mfma_f32_32x32x16_bf16 v[32:47], v[206:209], v[214:217], v[32:47]
	ds_read_b64_tr_b16 v[214:215], v184 offset:0x1600
	ds_read_b64_tr_b16 v[216:217], v184 offset:0x1e00
	v_mfma_f32_32x32x16_bf16 v[32:47], v[166:169], v[224:227], v[32:47]
	ds_read_b64_tr_b16 v[224:225], v184 offset:0x2600
	ds_read_b64_tr_b16 v[226:227], v184 offset:0x2e00
	v_mfma_f32_32x32x16_bf16 v[32:47], v[170:173], v[228:231], v[32:47]
	ds_read_b64_tr_b16 v[228:229], v184 offset:0x3600
	ds_read_b64_tr_b16 v[230:231], v184 offset:0x3e00
	s_waitcnt lgkmcnt(0)
	v_mfma_f32_32x32x16_bf16 v[16:31], v[160:163], v[210:213], v[16:31]
	v_max_f32_e32 v160, v80, v81
	v_max3_f32 v160, v160, v82, v83
	v_max3_f32 v160, v160, v84, v85
	v_max3_f32 v160, v160, v86, v87
	v_max3_f32 v160, v160, v88, v89
	v_max3_f32 v160, v160, v90, v91
	v_max3_f32 v160, v160, v92, v93
	v_mfma_f32_32x32x16_bf16 v[16:31], v[206:209], v[214:217], v[16:31]
	v_max3_f32 v160, v160, v94, v95
	v_max3_f32 v160, v160, v64, v65
	v_max3_f32 v160, v160, v66, v67
	v_max3_f32 v160, v160, v68, v69
	v_max3_f32 v160, v160, v70, v71
	v_max3_f32 v160, v160, v72, v73
	v_max3_f32 v160, v160, v74, v75
	v_max3_f32 v160, v160, v76, v77
	v_mfma_f32_32x32x16_bf16 v[16:31], v[166:169], v[224:227], v[16:31]
	v_max3_f32 v160, v160, v78, v79
	v_mov_b32_e32 v161, v160
	s_nop 1
	v_permlane32_swap_b32_e32 v160, v161
	v_max_f32_e32 v160, v160, v161
	v_sub_f32_e32 v161, v160, v164
	v_cmp_ge_f32_e32 vcc, s9, v161
	v_mfma_f32_32x32x16_bf16 v[16:31], v[170:173], v[228:231], v[16:31]
	s_cmp_eq_u64 vcc, exec
	s_cbranch_scc0 .Lattn_slow_a
	v_mov_b32_e32 v205, 1.0
	v_mov_b32_e32 v206, v164
	s_waitcnt vmcnt(4)
	ds_write_b128 v187, v[128:131]
	ds_write_b128 v187, v[136:139] offset:8192
	ds_write_b128 v185, v[132:135] offset:32768
	ds_write_b128 v185, v[140:143] offset:40960
